# conditional acquire elision: the split-phase wait + invalidate before the transposes is executed only by workgroups that actually have transpose items (the other half skips it)
# baseline (speedup 1.0000x reference)
.LBB0_723:
.Ltr_wait_done:
	s_mov_b64 exec, -1
	s_and_b64 vcc, exec, s[38:39]
	s_barrier
	s_cbranch_vccz .LBB0_725
	s_ashr_i32 s1, s24, 31
	s_lshr_b32 s1, s1, 29
	s_add_i32 s1, s24, s1
	s_ashr_i32 s10, s1, 3
	s_and_b32 s1, s1, -8
	s_ashr_i32 s0, s5, 3
	s_sub_i32 s1, s24, s1
	s_mul_i32 s0, s1, s0
	s_add_i32 s24, s0, s10
.LBB0_725:
	s_sub_i32 s0, s24, 0x80
	s_mov_b32 s82, 0x60000
	s_cmp_lt_i32 s0, 0
	s_nop 0
	s_cbranch_scc1 .LBB0_728
	v_readlane_b32 s98, v255, 22
	v_readlane_b32 s99, v255, 23
	s_and_b64 s[98:99], exec, s[98:99]
	s_mov_b64 exec, s[98:99]
	s_cbranch_execz .Ltr_wait_done2
	v_mov_b32_e32 v240, s70
	ds_read_b32 v241, v240 offset:4
	s_add_i32 s100, s4, 1
	v_mov_b32_e32 v242, 0x3480
	s_mov_b32 s101, 0
	s_waitcnt lgkmcnt(0)
	v_mul_lo_u32 v241, v241, s100

.Ltr_wait_done2:
	s_mov_b64 exec, -1
	s_barrier
	v_ashrrev_i32_e32 v38, 3, v193
	v_lshl_add_u32 v2, s58, 6, v38
	v_and_b32_e32 v3, 56, v153
	v_lshlrev_b32_e32 v0, 1, v3
	s_waitcnt vmcnt(3)
	v_add_u32_e32 v6, 8, v2
	s_waitcnt vmcnt(0)
	v_lshl_add_u64 v[18:19], s[16:17], 0, v[0:1]
	v_mad_i64_i32 v[22:23], s[16:17], v6, s8, 0
	v_add_u32_e32 v6, 16, v2
	v_mad_i64_i32 v[24:25], s[16:17], v6, s8, 0
	v_add_u32_e32 v6, 24, v2
	v_mad_i64_i32 v[26:27], s[16:17], v6, s8, 0
	v_add_u32_e32 v6, 32, v2
	s_mul_i32 s1, s25, 0x2100
	v_lshlrev_b32_e32 v4, 4, v193
	v_mad_i64_i32 v[28:29], s[16:17], v6, s8, 0
	v_add_u32_e32 v6, 40, v2
	s_add_i32 s1, s1, 0
	v_and_b32_e32 v4, 0x70, v4
	v_add_u32_e32 v39, 56, v38
	v_mad_i64_i32 v[30:31], s[16:17], v6, s8, 0
	v_add_u32_e32 v6, 48, v2
	v_add_u32_e32 v40, 8, v38
	v_add_u32_e32 v41, 16, v38
	v_add_u32_e32 v42, 24, v38
	v_add_u32_e32 v43, 32, v38
	v_add_u32_e32 v44, 40, v38
	v_add_u32_e32 v45, 48, v38
	v_add_u32_e32 v4, s1, v4
	v_lshl_add_u32 v5, v39, 1, s1
	s_lshl_b32 s10, s25, 4
	v_mad_i64_i32 v[32:33], s[16:17], v6, s8, 0
	v_lshl_add_u32 v6, v38, 1, s1
	v_lshl_add_u32 v7, v40, 1, s1
	v_lshl_add_u32 v8, v41, 1, s1
	v_lshl_add_u32 v9, v42, 1, s1
	v_lshl_add_u32 v10, v43, 1, s1
	v_lshl_add_u32 v11, v44, 1, s1
	v_lshl_add_u32 v12, v45, 1, s1
	s_lshl_b32 s1, s58, 7
	v_mad_i64_i32 v[20:21], s[16:17], v2, s8, 0
	v_add_u32_e32 v2, 56, v2
	s_add_u32 s14, s14, s1
	v_mad_i64_i32 v[34:35], s[16:17], v2, s8, 0
	s_addc_u32 s15, s15, 0
	s_movk_i32 s1, 0x4000
	s_movk_i32 s16, 0x84
	v_lshl_add_u64 v[36:37], s[14:15], 0, v[0:1]
	s_sub_i32 s10, s10, s1
	s_lshl_b32 s14, s24, 7
	v_mul_u32_u24_e32 v3, 0x84, v3
	v_mul_lo_u32 v2, v38, s16
	s_add_i32 s10, s10, s14
	s_nop 0
	v_add_u32_e32 v0, v4, v2
	v_add_u32_e32 v46, v6, v3
	v_add_u32_e32 v47, v7, v3
	v_add_u32_e32 v48, v8, v3
	v_add_u32_e32 v49, v9, v3
	v_add_u32_e32 v50, v10, v3
	v_add_u32_e32 v51, v11, v3
	v_add_u32_e32 v52, v12, v3
	v_add_u32_e32 v53, v5, v3
